# P5 tile rounds 1..4 rotated per XCD pair (different pairs stream different gate/up weight tiles at a time) on top of pair barrier + P1 rotation
# baseline (speedup 1.0000x reference)
;     __host__ __device__ bool next(int i, Unit& u) const {
;         const long L = (long)i * G + c; if (L >= nwg) return false;
;         int wgid = (int)L; { const int q = nwg / NXCD, r = nwg % NXCD, xcd = wgid % NXCD, off = wgid / NXCD; wgid = (xcd < r ? xcd * (q + 1) : r * (q + 1) + (xcd - r) * q) + off; }
;         const int nig = WGM * nN, gid = wgid / nig, fm = gid * WGM, gsz = (nM - fm) < WGM ? (nM - fm) : WGM;
;         u.pm = fm + ((wgid % nig) % gsz); u.pn = (wgid % nig) / gsz; return true;
.LBB0_579:
	s_add_i32 s59, s59, 1
	s_mul_i32 s4, s59, s79
	s_mul_hi_u32 s12, s59, s80
	s_add_i32 s12, s12, s4
	s_mul_i32 s4, s59, s80
	s_add_u32 s34, s4, s1
	s_addc_u32 s35, s12, s13
	v_mov_b64_e32 v[2:3], 0x580
	v_cmp_lt_i64_e64 s[38:39], s[34:35], v[2:3]
	v_mov_b64_e32 v[2:3], 0x57f
	v_cmp_gt_i64_e32 vcc, s[34:35], v[2:3]
	s_cbranch_vccnz .LBB0_581
	s_cmp_lg_u32 s98, 0
	s_cbranch_scc0 .Lrot5_skip
	s_cmp_gt_u32 s59, 4
	s_cbranch_scc1 .Lrot5_skip
	s_bfe_u32 s4, s1, 0x20001
	s_add_i32 s4, s4, s59
	s_sub_i32 s4, s4, 1
	s_and_b32 s4, s4, 3
	s_add_i32 s4, s4, 1
	s_mul_i32 s4, s4, s80
	s_add_i32 s34, s4, s1
.Lrot5_skip:
	s_ashr_i32 s4, s34, 31
	s_lshr_b32 s4, s4, 29
	s_add_i32 s4, s34, s4
	s_ashr_i32 s12, s4, 3
	s_and_b32 s4, s4, -8
	s_sub_i32 s4, s34, s4
	s_cmp_lt_i32 s4, 0
	s_movk_i32 s18, 0xb1
	s_cselect_b32 s18, s18, 0xb0
	s_mul_i32 s4, s4, s18
	s_add_i32 s4, s4, s12
	s_mul_hi_i32 s12, s4, 0x2e8ba2e9
	s_lshr_b32 s18, s12, 31
	s_ashr_i32 s12, s12, 5
	s_add_i32 s12, s12, s18
	s_lshl_b32 s19, s12, 3
	s_sub_i32 s18, 64, s19
	s_min_i32 s20, s18, 8
	s_abs_i32 s18, s20
	v_cvt_f32_u32_e32 v2, s18
	s_sub_i32 s25, 0, s18
	s_mulk_i32 s12, 0xb0
	s_sub_i32 s4, s4, s12
	v_rcp_iflag_f32_e32 v2, v2
	s_abs_i32 s12, s4
	s_xor_b32 s21, s4, s20
	s_ashr_i32 s21, s21, 31
	v_mul_f32_e32 v2, 0x4f7ffffe, v2
	v_cvt_u32_f32_e32 v2, v2
	s_nop 0
	v_readfirstlane_b32 s34, v2
	s_mul_i32 s25, s25, s34
	s_mul_hi_u32 s25, s34, s25
	s_add_i32 s34, s34, s25
	s_mul_hi_u32 s25, s12, s34
	s_mul_i32 s34, s25, s18
	s_sub_i32 s12, s12, s34
	s_add_i32 s35, s25, 1
	s_sub_i32 s34, s12, s18
	s_cmp_ge_u32 s12, s18
	s_cselect_b32 s25, s35, s25
	s_cselect_b32 s12, s34, s12
	s_add_i32 s34, s25, 1
	s_cmp_ge_u32 s12, s18
	s_cselect_b32 s12, s34, s25
	s_xor_b32 s12, s12, s21
	s_sub_i32 s18, s12, s21
	s_mul_i32 s12, s18, s20
	s_sub_i32 s4, s4, s12
	s_add_i32 s20, s19, s4
